# A-layer q/k/v projection output stored head-major (72 x [M][128]) so the sliding-window attention reads 256-byte rows of one head contiguously (row stride 256 B x dilation instead of 18 KB x dilation)
# baseline (speedup 1.0000x reference)
.LBB0_264:
	s_cmp_eq_u32 s21, 0
	s_cselect_b32 s32, 0x80, s20
	v_mov_b32_e32 v242, 0x80
	v_mov_b32_e32 v243, 0
	s_cbranch_scc0 .Lqkv_lay
	s_lshl_b32 s5, s5, 14
	v_mov_b32_e32 v242, 0x200000

.LBB0_267:
	s_add_i32 s4, s77, s43
	v_add_u32_e32 v62, s4, v152
	v_mad_u64_u32 v[54:55], s[4:5], v62, s32, 0
	v_ashrrev_i32_e32 v57, 31, v62
	v_mov_b32_e32 v56, v55
	v_mad_u64_u32 v[56:57], s[4:5], v57, s32, v[56:57]
	v_mov_b32_e32 v55, v56
	v_lshl_add_u64 v[56:57], v[54:55], 1, s[56:57]
	v_lshlrev_b64 v[54:55], 1, v[158:159]
	v_lshl_add_u64 v[60:61], v[56:57], 0, v[54:55]
	v_cvt_pk_bf16_f32 v56, v146, v147
	v_cvt_pk_bf16_f32 v57, v148, v149
	v_cvt_pk_bf16_f32 v58, v142, v143
	v_cvt_pk_bf16_f32 v59, v144, v145
	global_store_dwordx4 v[60:61], v[56:59], off sc1
	s_nop 1
	v_cvt_pk_bf16_f32 v56, v138, v139
	v_cvt_pk_bf16_f32 v57, v140, v141
	v_cvt_pk_bf16_f32 v58, v134, v135
	v_cvt_pk_bf16_f32 v59, v136, v137
	v_lshl_add_u64 v[60:61], v[242:243], 1, v[60:61]
	global_store_dwordx4 v[60:61], v[56:59], off sc1
	s_nop 1
	v_add_u32_e32 v56, 16, v62
	v_ashrrev_i32_e32 v59, 31, v56
	v_mad_u64_u32 v[56:57], s[4:5], v56, s32, 0
	v_mov_b32_e32 v58, v57
	v_mad_u64_u32 v[58:59], s[4:5], v59, s32, v[58:59]
	v_mov_b32_e32 v57, v58
	v_lshl_add_u64 v[56:57], v[56:57], 1, s[56:57]
	v_lshl_add_u64 v[60:61], v[56:57], 0, v[54:55]
	v_cvt_pk_bf16_f32 v56, v130, v131
	v_cvt_pk_bf16_f32 v57, v132, v133
	v_cvt_pk_bf16_f32 v58, v126, v127
	v_cvt_pk_bf16_f32 v59, v128, v129
	global_store_dwordx4 v[60:61], v[56:59], off sc1
	s_nop 1
	v_cvt_pk_bf16_f32 v56, v122, v123
	v_cvt_pk_bf16_f32 v57, v124, v125
	v_cvt_pk_bf16_f32 v58, v118, v119
	v_cvt_pk_bf16_f32 v59, v120, v121
	v_lshl_add_u64 v[60:61], v[242:243], 1, v[60:61]
	global_store_dwordx4 v[60:61], v[56:59], off sc1
	s_nop 1
	v_add_u32_e32 v56, 32, v62
	v_ashrrev_i32_e32 v59, 31, v56
	v_mad_u64_u32 v[56:57], s[4:5], v56, s32, 0
	v_mov_b32_e32 v58, v57
	v_mad_u64_u32 v[58:59], s[4:5], v59, s32, v[58:59]
	v_mov_b32_e32 v57, v58
	v_lshl_add_u64 v[56:57], v[56:57], 1, s[56:57]
	v_lshl_add_u64 v[60:61], v[56:57], 0, v[54:55]
	v_cvt_pk_bf16_f32 v56, v114, v115
	v_cvt_pk_bf16_f32 v57, v116, v117
	v_cvt_pk_bf16_f32 v58, v110, v111
	v_cvt_pk_bf16_f32 v59, v112, v113
	global_store_dwordx4 v[60:61], v[56:59], off sc1
	s_nop 1
	v_cvt_pk_bf16_f32 v56, v106, v107
	v_cvt_pk_bf16_f32 v57, v108, v109
	v_cvt_pk_bf16_f32 v58, v102, v103
	v_cvt_pk_bf16_f32 v59, v104, v105
	v_lshl_add_u64 v[60:61], v[242:243], 1, v[60:61]
	global_store_dwordx4 v[60:61], v[56:59], off sc1
	s_nop 1
	v_add_u32_e32 v56, 48, v62
	v_ashrrev_i32_e32 v59, 31, v56
	v_mad_u64_u32 v[56:57], s[4:5], v56, s32, 0
	v_mov_b32_e32 v58, v57
	v_mad_u64_u32 v[58:59], s[4:5], v59, s32, v[58:59]
	v_mov_b32_e32 v57, v58
	v_lshl_add_u64 v[56:57], v[56:57], 1, s[56:57]
	v_lshl_add_u64 v[60:61], v[56:57], 0, v[54:55]
	v_cvt_pk_bf16_f32 v56, v98, v99
	v_cvt_pk_bf16_f32 v57, v100, v101
	v_cvt_pk_bf16_f32 v58, v94, v95
	v_cvt_pk_bf16_f32 v59, v96, v97
	global_store_dwordx4 v[60:61], v[56:59], off sc1
	s_nop 1
	v_cvt_pk_bf16_f32 v56, v90, v91
	v_cvt_pk_bf16_f32 v57, v92, v93
	v_cvt_pk_bf16_f32 v58, v86, v87
	v_cvt_pk_bf16_f32 v59, v88, v89
	v_lshl_add_u64 v[60:61], v[242:243], 1, v[60:61]
	global_store_dwordx4 v[60:61], v[56:59], off sc1
	s_nop 1
	v_add_u32_e32 v56, 0x80, v62
	v_ashrrev_i32_e32 v59, 31, v56
	v_mad_u64_u32 v[56:57], s[4:5], v56, s32, 0
	v_mov_b32_e32 v58, v57
	v_mad_u64_u32 v[58:59], s[4:5], v59, s32, v[58:59]
	v_mov_b32_e32 v57, v58
	v_lshl_add_u64 v[56:57], v[56:57], 1, s[56:57]
	v_lshl_add_u64 v[60:61], v[56:57], 0, v[54:55]
	v_cvt_pk_bf16_f32 v56, v82, v83
	v_cvt_pk_bf16_f32 v57, v84, v85
	v_cvt_pk_bf16_f32 v58, v78, v79
	v_cvt_pk_bf16_f32 v59, v80, v81
	global_store_dwordx4 v[60:61], v[56:59], off sc1
	s_nop 1
	v_cvt_pk_bf16_f32 v56, v74, v75
	v_cvt_pk_bf16_f32 v57, v76, v77
	v_cvt_pk_bf16_f32 v58, v70, v71
	v_cvt_pk_bf16_f32 v59, v72, v73
	v_lshl_add_u64 v[60:61], v[242:243], 1, v[60:61]
	global_store_dwordx4 v[60:61], v[56:59], off sc1
	s_nop 1
	v_add_u32_e32 v56, 0x90, v62
	v_ashrrev_i32_e32 v59, 31, v56
	v_mad_u64_u32 v[56:57], s[4:5], v56, s32, 0
	v_mov_b32_e32 v58, v57
	v_mad_u64_u32 v[58:59], s[4:5], v59, s32, v[58:59]
	v_mov_b32_e32 v57, v58
	v_lshl_add_u64 v[56:57], v[56:57], 1, s[56:57]
	v_lshl_add_u64 v[60:61], v[56:57], 0, v[54:55]
	v_cvt_pk_bf16_f32 v56, v50, v51
	v_cvt_pk_bf16_f32 v57, v52, v53
	v_cvt_pk_bf16_f32 v58, v46, v47
	v_cvt_pk_bf16_f32 v59, v48, v49
	global_store_dwordx4 v[60:61], v[56:59], off sc1
	s_nop 1
	v_cvt_pk_bf16_f32 v56, v42, v43
	v_cvt_pk_bf16_f32 v57, v44, v45
	v_cvt_pk_bf16_f32 v58, v38, v39
	v_cvt_pk_bf16_f32 v59, v40, v41
	v_lshl_add_u64 v[60:61], v[242:243], 1, v[60:61]
	global_store_dwordx4 v[60:61], v[56:59], off sc1
	s_nop 1
	v_add_u32_e32 v56, 0xa0, v62
	v_ashrrev_i32_e32 v59, 31, v56
	v_mad_u64_u32 v[56:57], s[4:5], v56, s32, 0
	v_mov_b32_e32 v58, v57
	v_mad_u64_u32 v[58:59], s[4:5], v59, s32, v[58:59]
	v_mov_b32_e32 v57, v58
	v_lshl_add_u64 v[56:57], v[56:57], 1, s[56:57]
	v_lshl_add_u64 v[60:61], v[56:57], 0, v[54:55]
	v_cvt_pk_bf16_f32 v56, v34, v35
	v_cvt_pk_bf16_f32 v57, v36, v37
	v_cvt_pk_bf16_f32 v58, v30, v31
	v_cvt_pk_bf16_f32 v59, v32, v33
	global_store_dwordx4 v[60:61], v[56:59], off sc1
	s_nop 1
	v_cvt_pk_bf16_f32 v56, v26, v27
	v_cvt_pk_bf16_f32 v57, v28, v29
	v_cvt_pk_bf16_f32 v58, v22, v23
	v_cvt_pk_bf16_f32 v59, v24, v25
	v_lshl_add_u64 v[60:61], v[242:243], 1, v[60:61]
	global_store_dwordx4 v[60:61], v[56:59], off sc1
	s_nop 1
	v_add_u32_e32 v56, 0xb0, v62
	v_ashrrev_i32_e32 v59, 31, v56
	v_mad_u64_u32 v[56:57], s[4:5], v56, s32, 0
	v_mov_b32_e32 v58, v57
	v_mad_u64_u32 v[58:59], s[4:5], v59, s32, v[58:59]
	v_mov_b32_e32 v57, v58
	v_lshl_add_u64 v[56:57], v[56:57], 1, s[56:57]
	v_lshl_add_u64 v[58:59], v[56:57], 0, v[54:55]
	v_cvt_pk_bf16_f32 v54, v18, v19
	v_cvt_pk_bf16_f32 v55, v20, v21
	v_cvt_pk_bf16_f32 v56, v10, v11
	v_cvt_pk_bf16_f32 v57, v12, v13
	global_store_dwordx4 v[58:59], v[54:57], off sc1
	s_nop 1
	v_cvt_pk_bf16_f32 v54, v6, v7
	v_cvt_pk_bf16_f32 v55, v8, v9
	v_cvt_pk_bf16_f32 v56, v2, v3
	v_cvt_pk_bf16_f32 v57, v4, v5
	v_lshl_add_u64 v[58:59], v[242:243], 1, v[58:59]
	global_store_dwordx4 v[58:59], v[54:57], off sc1
	s_cbranch_execnz .LBB0_266

.LBB0_305:
	v_mad_u64_u32 v[142:143], s[8:9], v168, s32, 0
	v_mov_b32_e32 v0, v143
	v_mad_u64_u32 v[168:169], s[8:9], v169, s32, v[0:1]
	v_mov_b32_e32 v143, v168
	v_cvt_pk_bf16_f32 v168, v148, v149
	v_cvt_pk_bf16_f32 v169, v146, v147
	v_cvt_pk_bf16_f32 v170, v170, v171
	v_cvt_pk_bf16_f32 v171, v144, v145
	v_lshrrev_b32_e32 v144, 2, v175
	v_add_u32_e32 v144, 0x1a300, v144
	ds_read_b32 v144, v144 offset:4
	v_lshl_add_u64 v[142:143], v[142:143], 1, s[56:57]
	v_lshl_add_u64 v[142:143], v[158:159], 1, v[142:143]
	global_store_dwordx4 v[142:143], v[168:171], off sc1
	s_waitcnt lgkmcnt(0)
	v_mov_b32_e32 v0, v144
	v_pk_mul_f32 v[144:145], v[138:139], v[0:1] op_sel_hi:[1,0]
	v_pk_mul_f32 v[138:139], v[140:141], v[0:1] op_sel_hi:[1,0]
	v_pk_mul_f32 v[140:141], v[58:59], v[144:145]
	v_pk_mul_f32 v[144:145], v[134:135], v[0:1] op_sel_hi:[1,0]
	v_pk_mul_f32 v[134:135], v[136:137], v[0:1] op_sel_hi:[1,0]
	v_pk_mul_f32 v[138:139], v[60:61], v[138:139]
	v_pk_mul_f32 v[134:135], v[56:57], v[134:135]
	v_pk_mul_f32 v[136:137], v[54:55], v[144:145]
	s_and_b64 vcc, exec, s[6:7]
	s_cbranch_vccnz .LBB0_307
	ds_bpermute_b32 v144, v172, v140
	ds_bpermute_b32 v145, v172, v141
	ds_bpermute_b32 v146, v172, v136
	ds_bpermute_b32 v148, v172, v138
	ds_bpermute_b32 v149, v172, v139
	ds_bpermute_b32 v147, v172, v137
	ds_bpermute_b32 v168, v172, v134
	ds_bpermute_b32 v169, v172, v135
	s_waitcnt lgkmcnt(6)
	v_pk_mul_f32 v[144:145], v[164:165], v[144:145]
	s_waitcnt lgkmcnt(3)
	v_pk_mul_f32 v[148:149], v[166:167], v[148:149]
	v_pk_fma_f32 v[140:141], v[154:155], v[140:141], v[144:145]
	s_waitcnt lgkmcnt(2)
	v_pk_mul_f32 v[144:145], v[162:163], v[146:147]
	s_waitcnt lgkmcnt(0)
	v_pk_mul_f32 v[146:147], v[160:161], v[168:169]
	v_pk_fma_f32 v[138:139], v[156:157], v[138:139], v[148:149]
	v_pk_fma_f32 v[134:135], v[152:153], v[134:135], v[146:147]
	v_pk_fma_f32 v[136:137], v[150:151], v[136:137], v[144:145]
.LBB0_307:
	v_add_u32_e32 v152, 16, v173
	v_add_u32_e32 v150, s77, v152
	s_and_b64 vcc, exec, s[6:7]
	v_ashrrev_i32_e32 v151, 31, v150
	v_cvt_pk_bf16_f32 v144, v140, v141
	v_cvt_pk_bf16_f32 v145, v138, v139
	v_cvt_pk_bf16_f32 v146, v136, v137
	v_cvt_pk_bf16_f32 v147, v134, v135
	v_lshl_add_u64 v[142:143], v[242:243], 1, v[142:143]
	global_store_dwordx4 v[142:143], v[144:147], off sc1
	s_cbranch_vccz .LBB0_309
	s_nop 0
	v_mov_b32_e32 v146, 0
	v_mov_b32_e32 v138, 1.0
	v_mov_b32_e32 v139, v138
	v_mov_b32_e32 v140, v138
	v_mov_b32_e32 v141, v138
	v_mov_b32_e32 v134, v138
	v_mov_b32_e32 v135, v138
	v_mov_b32_e32 v136, v138
	v_mov_b32_e32 v137, v138
	v_mov_b32_e32 v147, v146
	v_mov_b32_e32 v148, v146
	v_mov_b32_e32 v149, v146
	v_mov_b32_e32 v144, v146
	v_mov_b32_e32 v145, v146
	v_mov_b32_e32 v142, v146
	v_mov_b32_e32 v143, v146
	s_branch .LBB0_310

.LBB0_312:
	v_mad_u64_u32 v[126:127], s[8:9], v150, s32, 0
	v_mov_b32_e32 v150, v127
	v_mad_u64_u32 v[150:151], s[8:9], v151, s32, v[150:151]
	v_add_u32_e32 v0, s33, v0
	v_mov_b32_e32 v127, v150
	v_cvt_pk_bf16_f32 v150, v132, v133
	v_cvt_pk_bf16_f32 v151, v130, v131
	v_cvt_pk_bf16_f32 v152, v152, v153
	v_cvt_pk_bf16_f32 v153, v128, v129
	v_lshrrev_b32_e32 v128, 2, v0
	v_add_u32_e32 v128, 0x1a300, v128
	ds_read_b32 v128, v128 offset:4
	v_lshl_add_u64 v[126:127], v[126:127], 1, s[56:57]
	v_lshl_add_u64 v[126:127], v[158:159], 1, v[126:127]
	global_store_dwordx4 v[126:127], v[150:153], off sc1
	s_waitcnt lgkmcnt(0)
	v_mov_b32_e32 v0, v128
	v_pk_mul_f32 v[128:129], v[122:123], v[0:1] op_sel_hi:[1,0]
	v_pk_mul_f32 v[122:123], v[124:125], v[0:1] op_sel_hi:[1,0]
	v_pk_mul_f32 v[124:125], v[58:59], v[128:129]
	v_pk_mul_f32 v[128:129], v[118:119], v[0:1] op_sel_hi:[1,0]
	v_pk_mul_f32 v[118:119], v[120:121], v[0:1] op_sel_hi:[1,0]
	v_pk_mul_f32 v[122:123], v[60:61], v[122:123]
	v_pk_mul_f32 v[118:119], v[56:57], v[118:119]
	v_pk_mul_f32 v[120:121], v[54:55], v[128:129]
	s_and_b64 vcc, exec, s[6:7]
	s_cbranch_vccnz .LBB0_314
	ds_bpermute_b32 v128, v172, v124
	ds_bpermute_b32 v129, v172, v125
	ds_bpermute_b32 v130, v172, v120
	ds_bpermute_b32 v132, v172, v122
	ds_bpermute_b32 v133, v172, v123
	ds_bpermute_b32 v131, v172, v121
	ds_bpermute_b32 v150, v172, v118
	ds_bpermute_b32 v151, v172, v119
	s_waitcnt lgkmcnt(6)
	v_pk_mul_f32 v[128:129], v[146:147], v[128:129]
	s_waitcnt lgkmcnt(3)
	v_pk_mul_f32 v[132:133], v[148:149], v[132:133]
	s_waitcnt vmcnt(2)
	v_pk_fma_f32 v[124:125], v[138:139], v[124:125], v[128:129]
	s_waitcnt lgkmcnt(2)
	v_pk_mul_f32 v[128:129], v[144:145], v[130:131]
	s_waitcnt lgkmcnt(0)
	v_pk_mul_f32 v[130:131], v[142:143], v[150:151]
	v_pk_fma_f32 v[122:123], v[140:141], v[122:123], v[132:133]
	s_waitcnt vmcnt(1)
	v_pk_fma_f32 v[118:119], v[136:137], v[118:119], v[130:131]
	v_pk_fma_f32 v[120:121], v[134:135], v[120:121], v[128:129]
.LBB0_314:
	v_cvt_pk_bf16_f32 v128, v124, v125
	v_cvt_pk_bf16_f32 v129, v122, v123
	s_nop 0
	v_cvt_pk_bf16_f32 v130, v120, v121
	v_cvt_pk_bf16_f32 v131, v118, v119
	v_lshl_add_u64 v[126:127], v[242:243], 1, v[126:127]
	global_store_dwordx4 v[126:127], v[128:131], off sc1
	s_waitcnt vmcnt(2)
	v_add_u32_e32 v136, 32, v173
	v_add_u32_e32 v134, s77, v136
	s_and_b64 vcc, exec, s[6:7]
	v_ashrrev_i32_e32 v135, 31, v134
	s_cbranch_vccz .LBB0_316
	v_mov_b32_e32 v130, 0
	v_mov_b32_e32 v122, 1.0
	v_mov_b32_e32 v123, v122
	v_mov_b32_e32 v124, v122
	v_mov_b32_e32 v125, v122
	v_mov_b32_e32 v118, v122
	v_mov_b32_e32 v119, v122
	v_mov_b32_e32 v120, v122
	v_mov_b32_e32 v121, v122
	v_mov_b32_e32 v131, v130
	v_mov_b32_e32 v132, v130
	v_mov_b32_e32 v133, v130
	v_mov_b32_e32 v128, v130
	v_mov_b32_e32 v129, v130
	v_mov_b32_e32 v126, v130
	v_mov_b32_e32 v127, v130
	s_branch .LBB0_317

.LBB0_319:
	v_mad_u64_u32 v[110:111], s[8:9], v134, s32, 0
	v_mov_b32_e32 v134, v111
	v_mad_u64_u32 v[134:135], s[8:9], v135, s32, v[134:135]
	v_add_u32_e32 v0, s33, v0
	v_mov_b32_e32 v111, v134
	v_cvt_pk_bf16_f32 v134, v116, v117
	v_cvt_pk_bf16_f32 v135, v114, v115
	v_cvt_pk_bf16_f32 v136, v136, v137
	v_cvt_pk_bf16_f32 v137, v112, v113
	v_lshrrev_b32_e32 v112, 2, v0
	v_add_u32_e32 v112, 0x1a300, v112
	ds_read_b32 v112, v112 offset:4
	v_lshl_add_u64 v[110:111], v[110:111], 1, s[56:57]
	v_lshl_add_u64 v[110:111], v[158:159], 1, v[110:111]
	global_store_dwordx4 v[110:111], v[134:137], off sc1
	s_waitcnt lgkmcnt(0)
	v_mov_b32_e32 v0, v112
	v_pk_mul_f32 v[112:113], v[106:107], v[0:1] op_sel_hi:[1,0]
	v_pk_mul_f32 v[106:107], v[108:109], v[0:1] op_sel_hi:[1,0]
	v_pk_mul_f32 v[108:109], v[58:59], v[112:113]
	v_pk_mul_f32 v[112:113], v[102:103], v[0:1] op_sel_hi:[1,0]
	v_pk_mul_f32 v[102:103], v[104:105], v[0:1] op_sel_hi:[1,0]
	v_pk_mul_f32 v[106:107], v[60:61], v[106:107]
	v_pk_mul_f32 v[102:103], v[56:57], v[102:103]
	v_pk_mul_f32 v[104:105], v[54:55], v[112:113]
	s_and_b64 vcc, exec, s[6:7]
	s_cbranch_vccnz .LBB0_321
	ds_bpermute_b32 v112, v172, v108
	ds_bpermute_b32 v113, v172, v109
	ds_bpermute_b32 v114, v172, v104
	ds_bpermute_b32 v116, v172, v106
	ds_bpermute_b32 v117, v172, v107
	ds_bpermute_b32 v115, v172, v105
	ds_bpermute_b32 v134, v172, v102
	ds_bpermute_b32 v135, v172, v103
	s_waitcnt lgkmcnt(6)
	v_pk_mul_f32 v[112:113], v[130:131], v[112:113]
	s_waitcnt lgkmcnt(3)
	v_pk_mul_f32 v[116:117], v[132:133], v[116:117]
	s_waitcnt vmcnt(2)
	v_pk_fma_f32 v[108:109], v[122:123], v[108:109], v[112:113]
	s_waitcnt lgkmcnt(2)
	v_pk_mul_f32 v[112:113], v[128:129], v[114:115]
	s_waitcnt lgkmcnt(0)
	v_pk_mul_f32 v[114:115], v[126:127], v[134:135]
	v_pk_fma_f32 v[106:107], v[124:125], v[106:107], v[116:117]
	s_waitcnt vmcnt(1)
	v_pk_fma_f32 v[102:103], v[120:121], v[102:103], v[114:115]
	v_pk_fma_f32 v[104:105], v[118:119], v[104:105], v[112:113]
.LBB0_321:
	s_waitcnt vmcnt(1)
	v_add_u32_e32 v120, 48, v173
	v_add_u32_e32 v118, s77, v120
	s_and_b64 vcc, exec, s[6:7]
	v_ashrrev_i32_e32 v119, 31, v118
	v_cvt_pk_bf16_f32 v112, v108, v109
	v_cvt_pk_bf16_f32 v113, v106, v107
	v_cvt_pk_bf16_f32 v114, v104, v105
	v_cvt_pk_bf16_f32 v115, v102, v103
	v_lshl_add_u64 v[110:111], v[242:243], 1, v[110:111]
	global_store_dwordx4 v[110:111], v[112:115], off sc1
	s_cbranch_vccz .LBB0_323
	s_nop 0
	v_mov_b32_e32 v114, 0
	v_mov_b32_e32 v106, 1.0
	v_mov_b32_e32 v107, v106
	v_mov_b32_e32 v108, v106
	v_mov_b32_e32 v109, v106
	v_mov_b32_e32 v102, v106
	v_mov_b32_e32 v103, v106
	v_mov_b32_e32 v104, v106
	v_mov_b32_e32 v105, v106
	v_mov_b32_e32 v115, v114
	v_mov_b32_e32 v116, v114
	v_mov_b32_e32 v117, v114
	v_mov_b32_e32 v112, v114
	v_mov_b32_e32 v113, v114
	v_mov_b32_e32 v110, v114
	v_mov_b32_e32 v111, v114
	s_branch .LBB0_324

.LBB0_326:
	v_mad_u64_u32 v[94:95], s[8:9], v118, s32, 0
	v_mov_b32_e32 v118, v95
	v_mad_u64_u32 v[118:119], s[8:9], v119, s32, v[118:119]
	v_add_u32_e32 v0, s33, v0
	v_mov_b32_e32 v95, v118
	v_cvt_pk_bf16_f32 v118, v100, v101
	v_cvt_pk_bf16_f32 v119, v98, v99
	v_cvt_pk_bf16_f32 v120, v120, v121
	v_cvt_pk_bf16_f32 v121, v96, v97
	v_lshrrev_b32_e32 v96, 2, v0
	v_add_u32_e32 v96, 0x1a300, v96
	ds_read_b32 v96, v96 offset:4
	v_lshl_add_u64 v[94:95], v[94:95], 1, s[56:57]
	v_lshl_add_u64 v[94:95], v[158:159], 1, v[94:95]
	global_store_dwordx4 v[94:95], v[118:121], off sc1
	s_waitcnt lgkmcnt(0)
	v_mov_b32_e32 v0, v96
	v_pk_mul_f32 v[96:97], v[90:91], v[0:1] op_sel_hi:[1,0]
	v_pk_mul_f32 v[90:91], v[92:93], v[0:1] op_sel_hi:[1,0]
	v_pk_mul_f32 v[92:93], v[58:59], v[96:97]
	v_pk_mul_f32 v[96:97], v[86:87], v[0:1] op_sel_hi:[1,0]
	v_pk_mul_f32 v[86:87], v[88:89], v[0:1] op_sel_hi:[1,0]
	v_pk_mul_f32 v[90:91], v[60:61], v[90:91]
	v_pk_mul_f32 v[86:87], v[56:57], v[86:87]
	v_pk_mul_f32 v[88:89], v[54:55], v[96:97]
	s_and_b64 vcc, exec, s[6:7]
	s_cbranch_vccnz .LBB0_328
	ds_bpermute_b32 v96, v172, v92
	ds_bpermute_b32 v97, v172, v93
	ds_bpermute_b32 v98, v172, v88
	ds_bpermute_b32 v100, v172, v90
	ds_bpermute_b32 v101, v172, v91
	ds_bpermute_b32 v99, v172, v89
	ds_bpermute_b32 v118, v172, v86
	ds_bpermute_b32 v119, v172, v87
	s_waitcnt lgkmcnt(6)
	v_pk_mul_f32 v[96:97], v[114:115], v[96:97]
	s_waitcnt lgkmcnt(3)
	v_pk_mul_f32 v[100:101], v[116:117], v[100:101]
	s_waitcnt vmcnt(2)
	v_pk_fma_f32 v[92:93], v[106:107], v[92:93], v[96:97]
	s_waitcnt lgkmcnt(2)
	v_pk_mul_f32 v[96:97], v[112:113], v[98:99]
	s_waitcnt lgkmcnt(0)
	v_pk_mul_f32 v[98:99], v[110:111], v[118:119]
	v_pk_fma_f32 v[90:91], v[108:109], v[90:91], v[100:101]
	s_waitcnt vmcnt(1)
	v_pk_fma_f32 v[86:87], v[104:105], v[86:87], v[98:99]
	v_pk_fma_f32 v[88:89], v[102:103], v[88:89], v[96:97]
.LBB0_328:
	v_cvt_pk_bf16_f32 v96, v92, v93
	v_cvt_pk_bf16_f32 v97, v90, v91
	s_nop 0
	v_cvt_pk_bf16_f32 v98, v88, v89
	v_cvt_pk_bf16_f32 v99, v86, v87
	v_lshl_add_u64 v[94:95], v[242:243], 1, v[94:95]
	global_store_dwordx4 v[94:95], v[96:99], off sc1
	s_waitcnt vmcnt(2)
	v_add_u32_e32 v104, 0x80, v173
	v_add_u32_e32 v102, s77, v104
	s_and_b64 vcc, exec, s[6:7]
	v_ashrrev_i32_e32 v103, 31, v102
	s_cbranch_vccz .LBB0_330
	v_mov_b32_e32 v98, 0
	v_mov_b32_e32 v90, 1.0
	v_mov_b32_e32 v91, v90
	v_mov_b32_e32 v92, v90
	v_mov_b32_e32 v93, v90
	v_mov_b32_e32 v86, v90
	v_mov_b32_e32 v87, v90
	v_mov_b32_e32 v88, v90
	v_mov_b32_e32 v89, v90
	v_mov_b32_e32 v99, v98
	v_mov_b32_e32 v100, v98
	v_mov_b32_e32 v101, v98
	v_mov_b32_e32 v96, v98
	v_mov_b32_e32 v97, v98
	v_mov_b32_e32 v94, v98
	v_mov_b32_e32 v95, v98
	s_branch .LBB0_331

.LBB0_333:
	v_mad_u64_u32 v[78:79], s[8:9], v102, s32, 0
	v_mov_b32_e32 v102, v79
	v_mad_u64_u32 v[102:103], s[8:9], v103, s32, v[102:103]
	v_add_u32_e32 v0, s33, v0
	v_mov_b32_e32 v79, v102
	v_cvt_pk_bf16_f32 v102, v84, v85
	v_cvt_pk_bf16_f32 v103, v82, v83
	v_cvt_pk_bf16_f32 v104, v104, v105
	v_cvt_pk_bf16_f32 v105, v80, v81
	v_lshrrev_b32_e32 v80, 2, v0
	v_add_u32_e32 v80, 0x1a300, v80
	ds_read_b32 v80, v80 offset:4
	v_lshl_add_u64 v[78:79], v[78:79], 1, s[56:57]
	v_lshl_add_u64 v[78:79], v[158:159], 1, v[78:79]
	global_store_dwordx4 v[78:79], v[102:105], off sc1
	s_waitcnt lgkmcnt(0)
	v_mov_b32_e32 v0, v80
	v_pk_mul_f32 v[80:81], v[74:75], v[0:1] op_sel_hi:[1,0]
	v_pk_mul_f32 v[74:75], v[76:77], v[0:1] op_sel_hi:[1,0]
	v_pk_mul_f32 v[76:77], v[58:59], v[80:81]
	v_pk_mul_f32 v[80:81], v[70:71], v[0:1] op_sel_hi:[1,0]
	v_pk_mul_f32 v[70:71], v[72:73], v[0:1] op_sel_hi:[1,0]
	v_pk_mul_f32 v[74:75], v[60:61], v[74:75]
	v_pk_mul_f32 v[70:71], v[56:57], v[70:71]
	v_pk_mul_f32 v[72:73], v[54:55], v[80:81]
	s_and_b64 vcc, exec, s[6:7]
	s_cbranch_vccnz .LBB0_335
	ds_bpermute_b32 v80, v172, v76
	ds_bpermute_b32 v81, v172, v77
	ds_bpermute_b32 v82, v172, v72
	ds_bpermute_b32 v84, v172, v74
	ds_bpermute_b32 v85, v172, v75
	ds_bpermute_b32 v83, v172, v73
	ds_bpermute_b32 v102, v172, v70
	ds_bpermute_b32 v103, v172, v71
	s_waitcnt lgkmcnt(6)
	v_pk_mul_f32 v[80:81], v[98:99], v[80:81]
	s_waitcnt lgkmcnt(3)
	v_pk_mul_f32 v[84:85], v[100:101], v[84:85]
	s_waitcnt vmcnt(2)
	v_pk_fma_f32 v[76:77], v[90:91], v[76:77], v[80:81]
	s_waitcnt lgkmcnt(2)
	v_pk_mul_f32 v[80:81], v[96:97], v[82:83]
	s_waitcnt lgkmcnt(0)
	v_pk_mul_f32 v[82:83], v[94:95], v[102:103]
	v_pk_fma_f32 v[74:75], v[92:93], v[74:75], v[84:85]
	s_waitcnt vmcnt(1)
	v_pk_fma_f32 v[70:71], v[88:89], v[70:71], v[82:83]
	v_pk_fma_f32 v[72:73], v[86:87], v[72:73], v[80:81]
.LBB0_335:
	s_waitcnt vmcnt(1)
	v_add_u32_e32 v88, 0x90, v173
	v_add_u32_e32 v86, s77, v88
	s_and_b64 vcc, exec, s[6:7]
	v_ashrrev_i32_e32 v87, 31, v86
	v_cvt_pk_bf16_f32 v80, v76, v77
	v_cvt_pk_bf16_f32 v81, v74, v75
	v_cvt_pk_bf16_f32 v82, v72, v73
	v_cvt_pk_bf16_f32 v83, v70, v71
	v_lshl_add_u64 v[78:79], v[242:243], 1, v[78:79]
	global_store_dwordx4 v[78:79], v[80:83], off sc1
	s_cbranch_vccz .LBB0_337
	s_nop 0
	v_mov_b32_e32 v82, 0
	v_mov_b32_e32 v74, 1.0
	v_mov_b32_e32 v75, v74
	v_mov_b32_e32 v76, v74
	v_mov_b32_e32 v77, v74
	v_mov_b32_e32 v70, v74
	v_mov_b32_e32 v71, v74
	v_mov_b32_e32 v72, v74
	v_mov_b32_e32 v73, v74
	v_mov_b32_e32 v83, v82
	v_mov_b32_e32 v84, v82
	v_mov_b32_e32 v85, v82
	v_mov_b32_e32 v80, v82
	v_mov_b32_e32 v81, v82
	v_mov_b32_e32 v78, v82
	v_mov_b32_e32 v79, v82
	s_branch .LBB0_338

.LBB0_340:
	v_mad_u64_u32 v[46:47], s[8:9], v86, s32, 0
	v_mov_b32_e32 v86, v47
	v_mad_u64_u32 v[86:87], s[8:9], v87, s32, v[86:87]
	v_add_u32_e32 v0, s33, v0
	v_mov_b32_e32 v47, v86
	v_cvt_pk_bf16_f32 v86, v52, v53
	v_cvt_pk_bf16_f32 v87, v50, v51
	v_cvt_pk_bf16_f32 v88, v88, v89
	v_cvt_pk_bf16_f32 v89, v48, v49
	v_lshrrev_b32_e32 v48, 2, v0
	v_add_u32_e32 v48, 0x1a300, v48
	ds_read_b32 v48, v48 offset:4
	v_lshl_add_u64 v[46:47], v[46:47], 1, s[56:57]
	v_lshl_add_u64 v[46:47], v[158:159], 1, v[46:47]
	global_store_dwordx4 v[46:47], v[86:89], off sc1
	s_waitcnt lgkmcnt(0)
	v_mov_b32_e32 v0, v48
	v_pk_mul_f32 v[48:49], v[42:43], v[0:1] op_sel_hi:[1,0]
	v_pk_mul_f32 v[42:43], v[44:45], v[0:1] op_sel_hi:[1,0]
	v_pk_mul_f32 v[44:45], v[58:59], v[48:49]
	v_pk_mul_f32 v[48:49], v[38:39], v[0:1] op_sel_hi:[1,0]
	v_pk_mul_f32 v[38:39], v[40:41], v[0:1] op_sel_hi:[1,0]
	v_pk_mul_f32 v[42:43], v[60:61], v[42:43]
	v_pk_mul_f32 v[38:39], v[56:57], v[38:39]
	v_pk_mul_f32 v[40:41], v[54:55], v[48:49]
	s_and_b64 vcc, exec, s[6:7]
	s_cbranch_vccnz .LBB0_342
	ds_bpermute_b32 v48, v172, v44
	ds_bpermute_b32 v49, v172, v45
	ds_bpermute_b32 v50, v172, v40
	ds_bpermute_b32 v52, v172, v42
	ds_bpermute_b32 v53, v172, v43
	ds_bpermute_b32 v51, v172, v41
	ds_bpermute_b32 v86, v172, v38
	ds_bpermute_b32 v87, v172, v39
	s_waitcnt lgkmcnt(6)
	v_pk_mul_f32 v[48:49], v[82:83], v[48:49]
	s_waitcnt lgkmcnt(3)
	v_pk_mul_f32 v[52:53], v[84:85], v[52:53]
	s_waitcnt vmcnt(2)
	v_pk_fma_f32 v[44:45], v[74:75], v[44:45], v[48:49]
	s_waitcnt lgkmcnt(2)
	v_pk_mul_f32 v[48:49], v[80:81], v[50:51]
	s_waitcnt lgkmcnt(0)
	v_pk_mul_f32 v[50:51], v[78:79], v[86:87]
	v_pk_fma_f32 v[42:43], v[76:77], v[42:43], v[52:53]
	s_waitcnt vmcnt(1)
	v_pk_fma_f32 v[38:39], v[72:73], v[38:39], v[50:51]
	v_pk_fma_f32 v[40:41], v[70:71], v[40:41], v[48:49]
.LBB0_342:
	v_cvt_pk_bf16_f32 v48, v44, v45
	v_cvt_pk_bf16_f32 v49, v42, v43
	s_nop 0
	v_cvt_pk_bf16_f32 v50, v40, v41
	v_cvt_pk_bf16_f32 v51, v38, v39
	v_lshl_add_u64 v[46:47], v[242:243], 1, v[46:47]
	global_store_dwordx4 v[46:47], v[48:51], off sc1
	s_waitcnt vmcnt(2)
	v_add_u32_e32 v72, 0xa0, v173
	v_add_u32_e32 v70, s77, v72
	s_and_b64 vcc, exec, s[6:7]
	v_ashrrev_i32_e32 v71, 31, v70
	s_cbranch_vccz .LBB0_344
	v_mov_b32_e32 v50, 0
	v_mov_b32_e32 v42, 1.0
	v_mov_b32_e32 v43, v42
	v_mov_b32_e32 v44, v42
	v_mov_b32_e32 v45, v42
	v_mov_b32_e32 v38, v42
	v_mov_b32_e32 v39, v42
	v_mov_b32_e32 v40, v42
	v_mov_b32_e32 v41, v42
	v_mov_b32_e32 v51, v50
	v_mov_b32_e32 v52, v50
	v_mov_b32_e32 v53, v50
	v_mov_b32_e32 v48, v50
	v_mov_b32_e32 v49, v50
	v_mov_b32_e32 v46, v50
	v_mov_b32_e32 v47, v50
	s_branch .LBB0_345

.LBB0_347:
	v_mad_u64_u32 v[30:31], s[8:9], v70, s32, 0
	v_mov_b32_e32 v70, v31
	v_mad_u64_u32 v[70:71], s[8:9], v71, s32, v[70:71]
	v_add_u32_e32 v0, s33, v0
	v_mov_b32_e32 v31, v70
	v_cvt_pk_bf16_f32 v70, v36, v37
	v_cvt_pk_bf16_f32 v71, v34, v35
	v_cvt_pk_bf16_f32 v72, v72, v73
	v_cvt_pk_bf16_f32 v73, v32, v33
	v_lshrrev_b32_e32 v32, 2, v0
	v_add_u32_e32 v32, 0x1a300, v32
	ds_read_b32 v32, v32 offset:4
	v_lshl_add_u64 v[30:31], v[30:31], 1, s[56:57]
	v_lshl_add_u64 v[30:31], v[158:159], 1, v[30:31]
	global_store_dwordx4 v[30:31], v[70:73], off sc1
	s_waitcnt lgkmcnt(0)
	v_mov_b32_e32 v0, v32
	v_pk_mul_f32 v[32:33], v[26:27], v[0:1] op_sel_hi:[1,0]
	v_pk_mul_f32 v[26:27], v[28:29], v[0:1] op_sel_hi:[1,0]
	v_pk_mul_f32 v[28:29], v[58:59], v[32:33]
	v_pk_mul_f32 v[32:33], v[22:23], v[0:1] op_sel_hi:[1,0]
	v_pk_mul_f32 v[22:23], v[24:25], v[0:1] op_sel_hi:[1,0]
	v_pk_mul_f32 v[26:27], v[60:61], v[26:27]
	v_pk_mul_f32 v[22:23], v[56:57], v[22:23]
	v_pk_mul_f32 v[24:25], v[54:55], v[32:33]
	s_and_b64 vcc, exec, s[6:7]
	s_cbranch_vccnz .LBB0_349
	ds_bpermute_b32 v32, v172, v28
	ds_bpermute_b32 v33, v172, v29
	ds_bpermute_b32 v34, v172, v24
	ds_bpermute_b32 v36, v172, v26
	ds_bpermute_b32 v37, v172, v27
	ds_bpermute_b32 v35, v172, v25
	ds_bpermute_b32 v70, v172, v22
	ds_bpermute_b32 v71, v172, v23
	s_waitcnt lgkmcnt(6)
	v_pk_mul_f32 v[32:33], v[50:51], v[32:33]
	s_waitcnt lgkmcnt(3)
	v_pk_mul_f32 v[36:37], v[52:53], v[36:37]
	s_waitcnt vmcnt(2)
	v_pk_fma_f32 v[28:29], v[42:43], v[28:29], v[32:33]
	s_waitcnt lgkmcnt(2)
	v_pk_mul_f32 v[32:33], v[48:49], v[34:35]
	s_waitcnt lgkmcnt(0)
	v_pk_mul_f32 v[34:35], v[46:47], v[70:71]
	v_pk_fma_f32 v[26:27], v[44:45], v[26:27], v[36:37]
	s_waitcnt vmcnt(1)
	v_pk_fma_f32 v[22:23], v[40:41], v[22:23], v[34:35]
	v_pk_fma_f32 v[24:25], v[38:39], v[24:25], v[32:33]
.LBB0_349:
	s_waitcnt vmcnt(1)
	v_add_u32_e32 v40, 0xb0, v173
	v_add_u32_e32 v38, s77, v40
	s_and_b64 vcc, exec, s[6:7]
	v_ashrrev_i32_e32 v39, 31, v38
	v_cvt_pk_bf16_f32 v32, v28, v29
	v_cvt_pk_bf16_f32 v33, v26, v27
	v_cvt_pk_bf16_f32 v34, v24, v25
	v_cvt_pk_bf16_f32 v35, v22, v23
	v_lshl_add_u64 v[30:31], v[242:243], 1, v[30:31]
	global_store_dwordx4 v[30:31], v[32:35], off sc1
	s_cbranch_vccz .LBB0_351
	s_nop 0
	v_mov_b32_e32 v34, 0
	v_mov_b32_e32 v26, 1.0
	v_mov_b32_e32 v27, v26
	v_mov_b32_e32 v28, v26
	v_mov_b32_e32 v29, v26
	v_mov_b32_e32 v22, v26
	v_mov_b32_e32 v23, v26
	v_mov_b32_e32 v24, v26
	v_mov_b32_e32 v25, v26
	v_mov_b32_e32 v35, v34
	v_mov_b32_e32 v36, v34
	v_mov_b32_e32 v37, v34
	v_mov_b32_e32 v32, v34
	v_mov_b32_e32 v33, v34
	v_mov_b32_e32 v30, v34
	v_mov_b32_e32 v31, v34
	s_branch .LBB0_352

.LBB0_354:
	v_mad_u64_u32 v[10:11], s[4:5], v38, s32, 0
	v_mov_b32_e32 v38, v11
	v_mad_u64_u32 v[38:39], s[4:5], v39, s32, v[38:39]
	v_add_u32_e32 v0, s33, v0
	v_mov_b32_e32 v11, v38
	v_cvt_pk_bf16_f32 v38, v20, v21
	v_cvt_pk_bf16_f32 v39, v18, v19
	v_cvt_pk_bf16_f32 v40, v40, v41
	v_cvt_pk_bf16_f32 v41, v12, v13
	v_lshrrev_b32_e32 v18, 2, v0
	v_add_u32_e32 v18, 0x1a300, v18
	ds_read_b32 v18, v18 offset:4
	v_lshl_add_u64 v[10:11], v[10:11], 1, s[56:57]
	v_lshl_add_u64 v[10:11], v[158:159], 1, v[10:11]
	global_store_dwordx4 v[10:11], v[38:41], off sc1
	s_waitcnt lgkmcnt(0)
	v_mov_b32_e32 v0, v18
	v_pk_mul_f32 v[12:13], v[6:7], v[0:1] op_sel_hi:[1,0]
	v_pk_mul_f32 v[6:7], v[8:9], v[0:1] op_sel_hi:[1,0]
	v_pk_mul_f32 v[8:9], v[58:59], v[12:13]
	v_pk_mul_f32 v[12:13], v[2:3], v[0:1] op_sel_hi:[1,0]
	v_pk_mul_f32 v[2:3], v[4:5], v[0:1] op_sel_hi:[1,0]
	v_pk_mul_f32 v[6:7], v[60:61], v[6:7]
	v_pk_mul_f32 v[2:3], v[56:57], v[2:3]
	v_pk_mul_f32 v[4:5], v[54:55], v[12:13]
	s_and_b64 vcc, exec, s[6:7]
	s_cbranch_vccnz .LBB0_356
	ds_bpermute_b32 v12, v172, v8
	ds_bpermute_b32 v13, v172, v9
	ds_bpermute_b32 v18, v172, v4
	ds_bpermute_b32 v20, v172, v6
	ds_bpermute_b32 v21, v172, v7
	ds_bpermute_b32 v19, v172, v5
	ds_bpermute_b32 v38, v172, v2
	ds_bpermute_b32 v39, v172, v3
	s_waitcnt lgkmcnt(6)
	v_pk_mul_f32 v[12:13], v[34:35], v[12:13]
	s_waitcnt lgkmcnt(3)
	v_pk_mul_f32 v[20:21], v[36:37], v[20:21]
	s_waitcnt vmcnt(2)
	v_pk_fma_f32 v[8:9], v[26:27], v[8:9], v[12:13]
	s_waitcnt lgkmcnt(2)
	v_pk_mul_f32 v[12:13], v[32:33], v[18:19]
	s_waitcnt lgkmcnt(0)
	v_pk_mul_f32 v[18:19], v[30:31], v[38:39]
	v_pk_fma_f32 v[6:7], v[28:29], v[6:7], v[20:21]
	s_waitcnt vmcnt(1)
	v_pk_fma_f32 v[2:3], v[24:25], v[2:3], v[18:19]
	v_pk_fma_f32 v[4:5], v[22:23], v[4:5], v[12:13]
.LBB0_356:
	v_cvt_pk_bf16_f32 v18, v8, v9
	v_cvt_pk_bf16_f32 v19, v6, v7
	s_nop 0
	v_cvt_pk_bf16_f32 v20, v4, v5
	v_cvt_pk_bf16_f32 v21, v2, v3
	v_lshl_add_u64 v[10:11], v[242:243], 1, v[10:11]
	global_store_dwordx4 v[10:11], v[18:21], off sc1
	s_andn2_b64 vcc, exec, s[80:81]
	s_mov_b64 s[4:5], -1
	s_cbranch_vccnz .LBB0_240

.LBB0_966:
	s_and_b64 vcc, exec, s[4:5]
	s_cbranch_vccz .LBB0_1175
	v_readlane_b32 s4, v255, 0
	v_readlane_b32 s5, v255, 1
	v_readlane_b32 s13, v255, 2
	s_mov_b32 s72, s97
	v_mbcnt_lo_u32_b32 v14, -1, 0
	v_mbcnt_hi_u32_b32 v14, -1, v14
	s_cmpk_gt_i32 s72, 0x5ff
	s_cbranch_scc1 .LBB0_1175
	s_load_dwordx2 s[0:1], s[4:5], 0xc0
	v_readlane_b32 s2, v255, 11
	v_lshlrev_b32_e32 v17, 3, v14
	v_and_b32_e32 v0, 0x78, v17
	v_add_u32_e32 v15, s2, v14
	s_waitcnt lgkmcnt(0)
	s_add_u32 s73, s0, 0x2a800000
	s_addc_u32 s74, s1, 0
	s_add_u32 s75, s0, 0x3c800000
	s_addc_u32 s76, s1, 0
	s_add_u32 s77, s0, 0x400000
	s_addc_u32 s78, s1, 0
	s_ashr_i32 s0, s72, 9
	s_lshl_b32 s6, s0, 1
	s_lshr_b32 s3, 16, s6
	s_and_b32 s1, s72, 15
	s_sub_i32 s2, 4, s6
	s_add_i32 s3, s3, -1
	s_lshr_b32 s2, s1, s2
	s_and_b32 s14, s3, s1
	s_lshl_b32 s1, s72, 5
	s_and_b32 s1, s1, 0x3000
	s_or_b32 s1, s2, s1
	s_add_i32 s2, s6, 8
	s_bfe_u32 s7, s72, 0x30004
	s_lshl_b64 s[2:3], s[14:15], s2
	s_add_u32 s2, s2, s1
	s_addc_u32 s3, s3, 0
	s_lshl_b64 s[4:5], s[2:3], 8
	s_add_u32 s8, s73, s4
	s_addc_u32 s9, s74, s5
	s_mul_i32 s4, s0, 0x6000000
	s_lshl_b32 s10, s7, 22
	s_add_i32 s4, s4, s10
	s_add_u32 s8, s8, s4
	s_addc_u32 s9, s9, 0
	s_lshl_b32 s1, s1, 8
	s_add_u32 s1, s73, s1
	s_addc_u32 s11, s74, 0
	s_add_u32 s1, s1, s4
	s_addc_u32 s4, s11, 0
	s_add_u32 s11, s1, 0x1fff800
	s_addc_u32 s12, s4, 0
	s_lshl_b32 s10, s7, 8
	s_add_u32 s46, s11, 0x800
	s_addc_u32 s47, s12, 0
	s_add_u32 s48, s11, 0x2000800
	s_addc_u32 s49, s12, 0
	s_ashr_i32 s1, s0, 31
	s_lshl_b64 s[4:5], s[0:1], 25
	s_add_u32 s20, s75, s4
	s_addc_u32 s21, s76, s5
	s_lshl_b64 s[4:5], s[2:3], 11
	s_add_u32 s4, s20, s4
	s_addc_u32 s5, s21, s5
	s_add_u32 s50, s4, s10
	s_addc_u32 s51, s5, 0
	s_lshl_b64 s[0:1], s[0:1], 19
	s_add_u32 s4, s77, s0
	s_addc_u32 s5, s78, s1
	s_lshl_b64 s[0:1], s[2:3], 5
	s_add_u32 s0, s4, s0
	s_addc_u32 s1, s5, s1
	s_lshl_b32 s2, s7, 2
	s_add_u32 s52, s0, s2
	s_addc_u32 s53, s1, 0
	s_lshl_b32 s82, s14, 8
	v_readfirstlane_b32 s0, v15
	s_lshl_b32 s79, 0x80, s6
	s_lshl_b32 s80, 0x400, s6
	s_lshl_b32 s81, 8, s6
	s_lshr_b32 s83, 0x1000, s6
	s_ashr_i32 s4, s0, 1
	s_add_i32 s0, s82, 0xffffff80
	s_cmp_lg_u32 s14, 0
	s_cselect_b32 s0, s0, 0
	s_mul_hi_u32 s1, s0, s79
	s_mul_i32 s0, s0, s79
	s_lshl_b64 s[0:1], s[0:1], 1
	s_add_u32 s2, s11, s0
	v_ashrrev_i32_e32 v218, 4, v15
	s_addc_u32 s3, s12, s1
	s_add_u32 s0, s48, s0
	s_waitcnt vmcnt(0)
	v_mul_lo_u32 v2, s79, v218
	s_addc_u32 s1, s49, s1
	v_or_b32_e32 v2, v2, v0
	s_lshl_b32 s5, 0x1000, s6
	v_mov_b32_e32 v3, v1
	v_add_u32_e32 v4, s5, v2
	v_lshlrev_b64 v[18:19], 1, v[2:3]
	v_mov_b32_e32 v5, v1
	v_lshlrev_b64 v[20:21], 1, v[4:5]
	v_lshl_add_u64 v[2:3], s[2:3], 0, v[18:19]
	v_lshl_add_u64 v[4:5], s[2:3], 0, v[20:21]
	global_load_dwordx4 v[196:199], v[2:3], off offset:2048
	global_load_dwordx4 v[200:203], v[4:5], off offset:2048
	v_mov_b32_e32 v2, s4
	s_movk_i32 s2, 0xffe0
	v_bfi_b32 v2, s2, v2, v14
	v_mul_lo_u32 v2, v2, s79
	v_lshrrev_b32_e32 v3, 2, v14
	v_and_or_b32 v2, v3, 8, v2
	v_mov_b32_e32 v3, v1
	v_lshl_add_u64 v[2:3], v[2:3], 1, s[8:9]
	global_load_dwordx4 v[176:179], v[2:3], off
	global_load_dwordx4 v[172:175], v[2:3], off offset:32
	global_load_dwordx4 v[168:171], v[2:3], off offset:64
	global_load_dwordx4 v[164:167], v[2:3], off offset:96
	global_load_dwordx4 v[160:163], v[2:3], off offset:128
	global_load_dwordx4 v[10:13], v[2:3], off offset:160
	global_load_dwordx4 v[6:9], v[2:3], off offset:192
	s_nop 0
	global_load_dwordx4 v[2:5], v[2:3], off offset:224
	v_lshl_add_u64 v[18:19], s[0:1], 0, v[18:19]
	v_lshl_add_u64 v[20:21], s[0:1], 0, v[20:21]
	global_load_dwordx4 v[204:207], v[18:19], off
	global_load_dwordx4 v[208:211], v[20:21], off
	s_movk_i32 s0, 0x70
	v_lshlrev_b32_e32 v21, 1, v0
	v_lshlrev_b32_e32 v20, 8, v218
	s_waitcnt vmcnt(0)
	v_and_b32_e32 v22, 0xfffff0, v218
	v_lshlrev_b32_e32 v23, 1, v218
	v_bitop3_b32 v25, v21, v15, s0 bitop3:0x78
	v_and_or_b32 v22, v23, 8, v22
	v_add3_u32 v23, 0, v20, v25
	v_add_u32_e32 v25, 32, v218
	v_and_b32_e32 v26, 0xfffff0, v25
	v_lshlrev_b32_e32 v25, 1, v25
	v_and_or_b32 v25, v25, 8, v26
	v_bfe_u32 v17, v17, 5, 2
	v_lshrrev_b32_e32 v24, 1, v218
	v_lshrrev_b32_e32 v22, 1, v22
	s_waitcnt vmcnt(0)
	v_lshrrev_b32_e32 v25, 1, v25
	v_and_b32_e32 v19, 0x70, v15
	v_or_b32_e32 v22, v22, v17
	v_or_b32_e32 v17, v25, v17
	v_and_b32_e32 v18, 63, v14
	v_lshlrev_b32_e32 v22, 9, v22
	v_lshlrev_b32_e32 v17, 9, v17
	v_bitop3_b32 v19, v21, v20, v19 bitop3:0xde
	v_and_b32_e32 v219, 31, v14
	v_bfe_u32 v220, v14, 5, 1
	v_lshlrev_b32_e32 v20, 3, v18
	s_cmp_lg_u32 0, -1
	s_cselect_b32 s0, 0, 0
	v_lshlrev_b32_e32 v221, 2, v220
	v_sub_u32_e32 v222, v219, v221
	v_lshlrev_b32_e32 v224, 8, v219
	ds_write_b128 v23, v[196:199] offset:32768
	ds_write_b128 v23, v[200:203] offset:40960
	v_and_b32_e32 v23, 3, v218
	v_and_or_b32 v23, v24, 4, v23
	v_lshlrev_b32_e32 v23, 6, v23
	v_and_b32_e32 v24, 48, v21
	v_lshlrev_b32_e32 v21, 4, v14
	v_or3_b32 v22, v22, v23, v24
	v_or3_b32 v17, v17, v23, v24
	v_and_b32_e32 v23, 0xc0, v21
	v_lshlrev_b32_e32 v14, 1, v14
	v_and_or_b32 v23, v20, 24, v23
	v_and_b32_e32 v14, 32, v14
	v_and_b32_e32 v20, 0x100, v20
	v_or3_b32 v14, v23, v14, v20
	v_add_u32_e32 v223, s0, v14
	v_lshlrev_b32_e32 v14, 4, v220
	v_and_b32_e32 v20, 0x70, v21
	v_or_b32_e32 v21, 32, v14
	v_xad_u32 v225, v14, v20, 0
	v_xad_u32 v226, v21, v20, 0
	v_or_b32_e32 v21, 64, v14
	v_or_b32_e32 v14, 0x60, v14
	v_xad_u32 v227, v21, v20, 0
	v_xad_u32 v228, v14, v20, 0
	v_cmp_gt_u32_e64 s[6:7], 32, v18
	v_lshlrev_b32_e32 v14, 3, v220
	v_add_u32_e32 v229, 0xffffff80, v222
	v_add_u32_e32 v230, 0, v22
	v_add_u32_e32 v231, 0, v17
	v_add_u32_e32 v232, 0, v19
	s_mov_b32 s3, s79
	s_waitcnt lgkmcnt(0)
	s_barrier
	s_branch .LBB0_970

.LBB0_970:
	s_add_i32 s20, s72, s13
	s_cmpk_lt_i32 s20, 0x600
	s_cselect_b64 s[56:57], -1, 0
	s_cmpk_gt_i32 s20, 0x5ff
	s_cselect_b64 s[54:55], -1, 0
	s_and_b64 vcc, exec, s[54:55]
	s_mov_b64 s[58:59], s[8:9]
	s_mov_b64 s[60:61], s[46:47]
	s_mov_b64 s[62:63], s[48:49]
	s_mov_b64 s[64:65], s[50:51]
	s_mov_b64 s[66:67], s[52:53]
	s_mov_b32 s0, s79
	s_mov_b32 s14, s3
	s_mov_b32 s1, s80
	s_mov_b32 s10, s81
	s_mov_b32 s11, s82
	s_mov_b32 s12, s83
	s_cbranch_vccnz .LBB0_972
	s_ashr_i32 s0, s20, 9
	s_lshl_b32 s2, s0, 1
	s_lshr_b32 s5, 16, s2
	s_and_b32 s1, s20, 15
	s_sub_i32 s4, 4, s2
	s_add_i32 s5, s5, -1
	s_lshr_b32 s4, s1, s4
	s_and_b32 s14, s5, s1
	s_lshl_b32 s1, s20, 5
	s_and_b32 s1, s1, 0x3000
	s_or_b32 s1, s4, s1
	s_add_i32 s4, s2, 8
	s_bfe_u32 s12, s20, 0x30004
	s_lshl_b64 s[4:5], s[14:15], s4
	s_add_u32 s4, s4, s1
	s_addc_u32 s5, s5, 0
	s_lshl_b64 s[10:11], s[4:5], 8
	s_add_u32 s21, s73, s10
	s_addc_u32 s22, s74, s11
	s_mul_i32 s10, s0, 0x6000000
	s_lshl_b32 s23, s12, 22
	s_add_i32 s10, s10, s23
	s_add_u32 s58, s21, s10
	s_addc_u32 s59, s22, 0
	s_lshl_b32 s1, s1, 8
	s_add_u32 s1, s73, s1
	s_addc_u32 s21, s74, 0
	s_add_u32 s1, s1, s10
	s_addc_u32 s10, s21, 0
	s_lshl_b32 s23, s12, 8
	s_add_u32 s60, s1, 0x2000000
	s_addc_u32 s61, s10, 0
	s_add_u32 s62, s1, 0x4000000
	s_addc_u32 s63, s10, 0
	s_ashr_i32 s1, s0, 31
	s_lshl_b64 s[10:11], s[0:1], 25
	s_add_u32 s21, s75, s10
	s_addc_u32 s22, s76, s11
	s_lshl_b64 s[10:11], s[4:5], 11
	s_add_u32 s10, s21, s10
	s_addc_u32 s11, s22, s11
	s_add_u32 s64, s10, s23
	s_addc_u32 s65, s11, 0
	s_lshl_b64 s[0:1], s[0:1], 19
	s_add_u32 s10, s77, s0
	s_addc_u32 s11, s78, s1
	s_lshl_b64 s[0:1], s[4:5], 5
	s_add_u32 s0, s10, s0
	s_addc_u32 s1, s11, s1
	s_lshl_b32 s4, s12, 2
	s_add_u32 s66, s0, s4
	s_addc_u32 s67, s1, 0
	s_lshl_b32 s0, 0x80, s2
	s_lshl_b32 s1, 0x400, s2
	s_lshl_b32 s10, 8, s2
	s_lshl_b32 s11, s14, 8
	s_lshr_b32 s12, 0x1000, s2
	s_mov_b32 s14, s0
